# scan helpers: lora biases w0/a0 enter as the C operand of the lora-out MFMAs, decay constants folded (12 fewer packed VALU ops per helper half-chunk)
# baseline (speedup 1.0000x reference)
;     __device__ __forceinline__ bf16* R(int i) const { return (bf16*)(ws + OFF_R0 + (size_t)i * RSZ); }
; __device__ __forceinline__ void phase_rwkv_scan(const Fr& F, int jr) {
;     ...
;         const int half = task & 1, h = (task >> 1) & 15, b = (task >> 5) & 3, s = task >> 7;
;         bf16* Yb = F.R(s);
;         const float* w0 = F.a->in[9] + (size_t)(jr * 2 + s) * D + h * 64; const float* a0 = F.a->in[12] + (size_t)(jr * 2 + s) * D + h * 64;
;         const float* kkw = F.a->in[15] + (size_t)jr * D + h * 64; const float* kaw = F.a->in[16] + (size_t)jr * D + h * 64;
;         f32x2 S01 = {0.f, 0.f}, S23 = {0.f, 0.f};
;         const int ks = 4 * l15, rloc = 4 * wave + lq;
;         const int pt = wave & 3, ht0 = (wave >> 2) * 2;
;         const int p1 = pt * 16 + l15;
;         const int p2 = tid >> 3, j8 = tid & 7, hk0 = 8 * j8;
;         bf16x8 Bw[2][2], Ba[2][2]; float w0v[2], a0v[2];
; #pragma unroll
;         for (int hh = 0; hh < 2; ++hh) { const int hk = (ht0 + hh) * 16 + l15, e = h * 64 + hk; w0v[hh] = w0[hk]; a0v[hh] = a0[hk];
; #pragma unroll
;             for (int kst = 0; kst < 2; ++kst) { Bw[hh][kst] = *(const bf16x8*)(L2T + ((size_t)s * D + e) * 64 + 32 * kst + 8 * lq); Ba[hh][kst] = *(const bf16x8*)(L2T + ((size_t)(2 + s) * D + e) * 64 + 32 * kst + 8 * lq); } }
;         float kkc[8], kac[8], rkc[8];
; #pragma unroll
;         for (int i = 0; i < 8; ++i) { kkc[i] = kkw[hk0 + i]; kac[i] = kaw[hk0 + i]; rkc[i] = F.a->in[17][(size_t)jr * D + h * 64 + hk0 + i]; }
;         float* Bon = (float*)(F.ws + OFF_R0 + 6 * RSZ + 16 * MiB);
;         bf16x8 Aw[2], Aa[2]; u32x4 kw, rw; u32x2 vw;
;         {   const size_t row1 = (size_t)b * TB + tokof(s, p1), row2 = (size_t)b * TB + tokof(s, p2);
; #pragma unroll
;             for (int kst = 0; kst < 2; ++kst) { Aw[kst] = *(const bf16x8*)(LM + row1 * 256 + 64 * s + 32 * kst + 8 * lq); Aa[kst] = *(const bf16x8*)(LM + row1 * 256 + 128 + 64 * s + 32 * kst + 8 * lq); }
;             kw = *(const u32x4*)(Kb + row2 * D + h * 64 + hk0); rw = *(const u32x4*)(Rb + row2 * D + h * 64 + hk0); vw = *(const u32x2*)(Vb + row2 * D + h * 64 + 32 * half + 4 * j8); }
.Lrw0_helper:
	s_sub_i32 s17, s68, 4
	v_mov_b32_e32 v122, 0xbfb8aa3b
	v_mov_b32_e32 v123, 0xbfb8aa3b
	v_mov_b32_e32 v124, 0xbf60028a
	v_mov_b32_e32 v125, 0xbf60028a
	v_mov_b32_e32 v126, 0x3fb8aa3b
	v_mov_b32_e32 v127, 0x3fb8aa3b
	s_and_b32 s14, s17, 1
	s_lshr_b32 s15, s17, 1
	v_and_b32_e32 v196, 15, v130
	v_lshrrev_b32_e32 v217, 4, v130
	s_lshl_b32 s17, s14, 4
	v_add_u32_e32 v216, s17, v196
	v_mov_b32_e32 v218, v216
	s_cmp_eq_u32 s6, 0
	s_cbranch_scc1 .Lrw0_hdir0
	v_sub_u32_e32 v218, 0, v216
.Lrw0_hdir0:
	s_mul_i32 s16, s7, 0x1100
	v_lshlrev_b32_e32 v221, 4, v217
	s_lshl_b32 s17, s15, 6
	v_lshl_add_u32 v219, v217, 3, s17
	s_xor_b32 s18, s17, 64
	v_lshl_add_u32 v220, v217, 3, s18
	s_lshl_b32 s17, s15, 7
	v_mul_u32_u24_e32 v197, 0x110, v216
	v_add_u32_e32 v197, s17, v197
	v_lshl_add_u32 v222, v217, 4, v197
	v_lshrrev_b32_e32 v201, 1, v216
	v_mul_u32_u24_e32 v201, 0x210, v201
	v_and_b32_e32 v203, 1, v216
	v_lshl_add_u32 v201, v203, 3, v201
	s_lshl_b32 s18, s15, 8
	v_lshl_add_u32 v203, v217, 6, s18
	v_add_u32_e32 v223, v201, v203
	s_lshl_b32 s17, s6, 7
	s_add_u32 s20, s26, 0xde00000
	s_addc_u32 s21, s27, 0
	s_add_u32 s20, s20, s17
	s_addc_u32 s21, s21, 0
	s_lshl_b32 s17, s8, 7
	s_add_u32 s22, s26, 0xbc00000
	s_addc_u32 s23, s27, 0
	s_add_u32 s22, s22, s17
	s_addc_u32 s23, s23, 0
	s_add_u32 s24, s26, 0x9a00000
	s_addc_u32 s25, s27, 0
	s_add_u32 s24, s24, s17
	s_addc_u32 s25, s25, 0
	s_lshl_b32 s18, s9, 6
	s_add_i32 s17, s17, s18
	s_lshl_b32 s18, s15, 5
	s_add_i32 s17, s17, s18
	s_add_u32 s42, s26, 0x5600000
	s_addc_u32 s43, s27, 0
	s_add_u32 s42, s42, s17
	s_addc_u32 s43, s43, 0
	s_lshl_b32 s17, s8, 2
	s_add_u32 s44, s26, 0xee00000
	s_addc_u32 s45, s27, 0
	s_add_u32 s44, s44, s17
	s_addc_u32 s45, s45, 0
	s_cmp_eq_u32 s15, 0
	s_cselect_b32 s58, 1, 0
	s_xor_b32 s59, s6, s9
	s_load_dwordx2 s[46:47], s[0:1], 0x48
	s_load_dwordx2 s[48:49], s[0:1], 0x60
	s_load_dwordx2 s[50:51], s[0:1], 0x78
	s_load_dwordx2 s[52:53], s[0:1], 0x80
	s_load_dwordx2 s[54:55], s[0:1], 0x88
	s_lshl_b32 s17, s8, 8
	s_lshl_b32 s18, s15, 7
	s_add_i32 s19, s17, s18
	v_lshl_add_u32 v198, v217, 4, s19
	s_xor_b32 s18, s18, 128
	s_add_i32 s19, s17, s18
	v_lshl_add_u32 v199, v217, 4, s19
	s_waitcnt lgkmcnt(0)
	s_lshl_b32 s17, s6, 12
	s_add_u32 s46, s46, s17
	s_addc_u32 s47, s47, 0
	s_add_u32 s48, s48, s17
	s_addc_u32 s49, s49, 0
	global_load_dwordx4 v[32:35], v198, s[46:47] offset:0
	global_load_dwordx4 v[40:43], v198, s[48:49] offset:0
	global_load_dwordx4 v[64:67], v198, s[52:53] offset:0
	global_load_dwordx4 v[36:39], v198, s[46:47] offset:64
	global_load_dwordx4 v[44:47], v198, s[48:49] offset:64
	global_load_dwordx4 v[68:71], v198, s[52:53] offset:64
	global_load_dwordx4 v[48:51], v198, s[50:51] offset:0
	global_load_dwordx4 v[72:75], v198, s[54:55] offset:0
	global_load_dwordx4 v[52:55], v198, s[50:51] offset:64
	global_load_dwordx4 v[76:79], v198, s[54:55] offset:64
	global_load_dwordx4 v[56:59], v199, s[50:51] offset:0
	global_load_dwordx4 v[80:83], v199, s[54:55] offset:0
	global_load_dwordx4 v[60:63], v199, s[50:51] offset:64
	global_load_dwordx4 v[84:87], v199, s[54:55] offset:64
	s_lshl_b32 s17, s8, 6
	s_lshl_b32 s18, s15, 5
	s_add_i32 s17, s17, s18
	v_add_u32_e32 v200, s17, v196
	v_lshlrev_b32_e32 v200, 7, v200
	v_add_u32_e32 v200, v200, v221
	s_lshl_b32 s17, s6, 17
	s_add_u32 s46, s26, 0x200000
	s_addc_u32 s47, s27, 0
	s_add_u32 s46, s46, s17
	s_addc_u32 s47, s47, 0
	s_add_u32 s48, s46, 0x40000
	s_addc_u32 s49, s47, 0
	global_load_dwordx4 v[0:3], v200, s[46:47] offset:0
	global_load_dwordx4 v[16:19], v200, s[48:49] offset:0
	global_load_dwordx4 v[4:7], v200, s[46:47] offset:64
	global_load_dwordx4 v[20:23], v200, s[48:49] offset:64
	global_load_dwordx4 v[8:11], v200, s[46:47] offset:2048
	global_load_dwordx4 v[24:27], v200, s[48:49] offset:2048
	global_load_dwordx4 v[12:15], v200, s[46:47] offset:2112
	global_load_dwordx4 v[28:31], v200, s[48:49] offset:2112
	s_mov_b32 s10, 0
	s_mov_b32 s11, 0
	s_lshl_b32 s17, s10, 5
	s_cmp_lt_u32 s10, 8
	s_movk_i32 s18, 0x11ff
	s_cselect_b32 s18, 0xff, s18
	s_sub_i32 s18, s18, s17
	s_cmp_eq_u32 s6, 0
	s_cselect_b32 s17, s17, s18
	s_add_i32 s17, s17, s16
	v_add_u32_e32 v231, s17, v218
	v_lshl_add_u32 v226, v231, 9, v221
	v_lshl_add_u32 v227, v231, 11, v219
	v_lshl_add_u32 v228, v231, 11, v220
	v_lshlrev_b32_e32 v229, 3, v217
	v_lshl_add_u32 v229, v231, 11, v229
	v_lshlrev_b32_e32 v230, 6, v231
	global_load_dwordx4 v[88:91], v226, s[20:21]
	global_load_dwordx4 v[92:95], v226, s[20:21] offset:64
	global_load_dwordx4 v[96:99], v226, s[20:21] offset:256
	global_load_dwordx4 v[100:103], v226, s[20:21] offset:320
	global_load_dwordx2 v[104:105], v227, s[22:23] offset:0
	global_load_dwordx2 v[106:107], v227, s[22:23] offset:32
	global_load_dwordx2 v[108:109], v228, s[22:23] offset:0
	global_load_dwordx2 v[110:111], v228, s[22:23] offset:32
	global_load_dwordx2 v[112:113], v227, s[24:25] offset:0
	global_load_dwordx2 v[114:115], v227, s[24:25] offset:32
	global_load_dwordx2 v[116:117], v228, s[24:25] offset:0
	global_load_dwordx2 v[118:119], v228, s[24:25] offset:32
	global_load_dwordx2 v[120:121], v229, s[42:43]
	v_mov_b32_e32 v224, v222
	v_mov_b32_e32 v225, v223
	v_mov_b32_e32 v202, v230
	s_and_b32 s17, s10, 3
	s_cmp_eq_u32 s17, s59
	s_cselect_b32 s32, s58, 0
	s_waitcnt vmcnt(0)
; __device__ __forceinline__ float sigm(float x) { return __builtin_amdgcn_rcpf(1.f + __expf(-x)); }
; #define LDS_BAR() asm volatile("s_waitcnt lgkmcnt(0)\n\ts_barrier" ::: "memory")
; __device__ __forceinline__ void phase_rwkv_scan(const Fr& F, int jr) {
;     ...
;                 for (int kst = 0; kst < 2; ++kst) { cw = __builtin_amdgcn_mfma_f32_16x16x32_bf16(Aw[kst], Bw[hh][kst], cw, 0, 0, 0); ca = __builtin_amdgcn_mfma_f32_16x16x32_bf16(Aa[kst], Ba[hh][kst], ca, 0, 0, 0); }
; #pragma unroll
;                 for (int reg = 0; reg < 4; ++reg) { const int pp = pt * 16 + lq * 4 + reg;
;                     Wv[pp * 64 + hk] = __expf(-0.60653066f * sigm(w0v[hh] + cw[reg]));
;                     Av[pp * 64 + hk] = sigm(a0v[hh] + ca[reg]); }
;             }
;             LDS_BAR();
;             {
;                 const float kr[8] = {lo_bf(kw.x), hi_bf(kw.x), lo_bf(kw.y), hi_bf(kw.y), lo_bf(kw.z), hi_bf(kw.z), lo_bf(kw.w), hi_bf(kw.w)};
;                 const float rr[8] = {lo_bf(rw.x), hi_bf(rw.x), lo_bf(rw.y), hi_bf(rw.y), lo_bf(rw.z), hi_bf(rw.z), lo_bf(rw.w), hi_bf(rw.w)};
;                 float kq[8]; float ss = 0.f, bon = 0.f;
; #pragma unroll
;                 for (int i = 0; i < 8; ++i) { kq[i] = kr[i] * kkc[i]; ss += kq[i] * kq[i]; bon += rr[i] * kr[i] * rkc[i]; }
	v_mfma_f32_16x16x32_bf16 v[136:139], v[0:3], v[88:91], v[32:35]
	v_mfma_f32_16x16x32_bf16 v[136:139], v[4:7], v[92:95], v[136:139]
	v_mfma_f32_16x16x32_bf16 v[140:143], v[8:11], v[88:91], v[36:39]
	v_mfma_f32_16x16x32_bf16 v[140:143], v[12:15], v[92:95], v[140:143]
	v_mfma_f32_16x16x32_bf16 v[144:147], v[16:19], v[96:99], v[40:43]
	v_mfma_f32_16x16x32_bf16 v[144:147], v[20:23], v[100:103], v[144:147]
	v_mfma_f32_16x16x32_bf16 v[148:151], v[24:27], v[96:99], v[44:47]
	v_mfma_f32_16x16x32_bf16 v[148:151], v[28:31], v[100:103], v[148:151]
	v_lshlrev_b32_e32 v152, 16, v104
	v_and_b32_e32 v153, 0xffff0000, v104
	v_lshlrev_b32_e32 v154, 16, v105
	v_and_b32_e32 v155, 0xffff0000, v105
	v_lshlrev_b32_e32 v156, 16, v106
	v_and_b32_e32 v157, 0xffff0000, v106
	v_lshlrev_b32_e32 v158, 16, v107
	v_and_b32_e32 v159, 0xffff0000, v107
	v_lshlrev_b32_e32 v160, 16, v108
	v_and_b32_e32 v161, 0xffff0000, v108
	v_lshlrev_b32_e32 v162, 16, v109
	v_and_b32_e32 v163, 0xffff0000, v109
	v_lshlrev_b32_e32 v164, 16, v110
	v_and_b32_e32 v165, 0xffff0000, v110
	v_lshlrev_b32_e32 v166, 16, v111
	v_and_b32_e32 v167, 0xffff0000, v111
	v_lshlrev_b32_e32 v168, 16, v112
	v_and_b32_e32 v169, 0xffff0000, v112
	v_lshlrev_b32_e32 v170, 16, v113
	v_and_b32_e32 v171, 0xffff0000, v113
	v_lshlrev_b32_e32 v172, 16, v114
	v_and_b32_e32 v173, 0xffff0000, v114
	v_lshlrev_b32_e32 v174, 16, v115
	v_and_b32_e32 v175, 0xffff0000, v115
	v_lshlrev_b32_e32 v192, 16, v120
	v_and_b32_e32 v193, 0xffff0000, v120
	v_lshlrev_b32_e32 v194, 16, v121
	v_and_b32_e32 v195, 0xffff0000, v121
	v_pk_mul_f32 v[176:177], v[152:153], v[48:49]
	v_pk_mul_f32 v[178:179], v[154:155], v[50:51]
	v_pk_mul_f32 v[180:181], v[156:157], v[52:53]
	v_pk_mul_f32 v[182:183], v[158:159], v[54:55]
	v_pk_mul_f32 v[184:185], v[160:161], v[56:57]
	v_pk_mul_f32 v[186:187], v[162:163], v[58:59]
	v_pk_mul_f32 v[188:189], v[164:165], v[60:61]
	v_pk_mul_f32 v[190:191], v[166:167], v[62:63]
	v_pk_mul_f32 v[196:197], v[176:177], v[176:177]
	v_pk_mul_f32 v[198:199], v[178:179], v[178:179]
	v_pk_fma_f32 v[196:197], v[180:181], v[180:181], v[196:197]
	v_pk_fma_f32 v[198:199], v[182:183], v[182:183], v[198:199]
	v_pk_fma_f32 v[196:197], v[184:185], v[184:185], v[196:197]
	v_pk_fma_f32 v[198:199], v[186:187], v[186:187], v[198:199]
	v_pk_fma_f32 v[196:197], v[188:189], v[188:189], v[196:197]
	v_pk_fma_f32 v[198:199], v[190:191], v[190:191], v[198:199]
	s_nop 0
	v_pk_add_f32 v[196:197], v[196:197], v[198:199]
	s_cmp_eq_u32 s32, 0
	s_cbranch_scc1 .Lrw0_hnbc0
	v_mul_f32_e32 v208, v168, v152
	v_mul_f32_e32 v209, v169, v153
	v_mul_f32_e32 v210, v170, v154
	v_mul_f32_e32 v211, v171, v155
	v_mul_f32_e32 v234, v72, v208
	v_fmac_f32_e32 v234, v73, v209
	v_fmac_f32_e32 v234, v74, v210
	v_fmac_f32_e32 v234, v75, v211
	v_mul_f32_e32 v208, v172, v156
	v_mul_f32_e32 v209, v173, v157
	v_mul_f32_e32 v210, v174, v158
	v_mul_f32_e32 v211, v175, v159
	v_fmac_f32_e32 v234, v76, v208
	v_fmac_f32_e32 v234, v77, v209
	v_fmac_f32_e32 v234, v78, v210
	v_fmac_f32_e32 v234, v79, v211
	v_lshlrev_b32_e32 v204, 16, v116
	v_and_b32_e32 v205, 0xffff0000, v116
	v_lshlrev_b32_e32 v206, 16, v117
	v_and_b32_e32 v207, 0xffff0000, v117
	v_mul_f32_e32 v208, v204, v160
	v_mul_f32_e32 v209, v205, v161
	v_mul_f32_e32 v210, v206, v162
	v_mul_f32_e32 v211, v207, v163
	v_fmac_f32_e32 v234, v80, v208
	v_fmac_f32_e32 v234, v81, v209
	v_fmac_f32_e32 v234, v82, v210
	v_fmac_f32_e32 v234, v83, v211
	v_lshlrev_b32_e32 v204, 16, v118
	v_and_b32_e32 v205, 0xffff0000, v118
	v_lshlrev_b32_e32 v206, 16, v119
	v_and_b32_e32 v207, 0xffff0000, v119
	v_mul_f32_e32 v208, v204, v164
	v_mul_f32_e32 v209, v205, v165
	v_mul_f32_e32 v210, v206, v166
	v_mul_f32_e32 v211, v207, v167
	v_fmac_f32_e32 v234, v84, v208
	v_fmac_f32_e32 v234, v85, v209
	v_fmac_f32_e32 v234, v86, v210
	v_fmac_f32_e32 v234, v87, v211

; __device__ __forceinline__ float sigm(float x) { return __builtin_amdgcn_rcpf(1.f + __expf(-x)); }
; template <int CTRL> __device__ __forceinline__ float dppf(float x) { return __builtin_bit_cast(float, __builtin_amdgcn_update_dpp(0, __builtin_bit_cast(int, x), CTRL, 0xF, 0xF, false)); }
; __device__ __forceinline__ void phase_rwkv_scan(const Fr& F, int jr) {
;     ...
;                     Wv[pp * 64 + hk] = __expf(-0.60653066f * sigm(w0v[hh] + cw[reg]));
;                     Av[pp * 64 + hk] = sigm(a0v[hh] + ca[reg]); }
;     ...
;                 ss += dppf<0xB1>(ss); ss += dppf<0x4E>(ss); ss += dppf<0x141>(ss); bon += dppf<0xB1>(bon); bon += dppf<0x4E>(bon); bon += dppf<0x141>(bon);
;                 if (s == 0 && half == 0 && j8 == 0) Bon[((size_t)b * TB + tokof(s, chunk * 64 + p2)) * 16 + h] = bon;
;                 const float inv = 1.f / fmaxf(sqrtf(ss), 1e-12f);
.Lrw0_hnl0:
	v_mov_b32_e32 v196, v232
	s_nop 1
	v_permlane16_swap_b32_e32 v232, v196
	s_nop 1
	v_add_f32_e32 v232, v232, v196
	v_mov_b32_e32 v196, v232
	s_nop 1
	v_permlane32_swap_b32_e32 v232, v196
	s_nop 1
	v_add_f32_e32 v232, v232, v196
	v_mul_f32_e32 v197, 0x4f800000, v232
	v_mov_b32_e32 v198, 0xf800000
	v_cmp_gt_f32_e32 vcc, v198, v232
	s_nop 1
	v_cndmask_b32_e32 v196, v232, v197, vcc
	v_sqrt_f32_e32 v197, v196
	s_nop 0
	v_add_u32_e32 v198, -1, v197
	v_fma_f32 v200, -v198, v197, v196
	v_add_u32_e32 v199, 1, v197
	v_cmp_ge_f32_e64 s[56:57], 0, v200
	s_nop 1
	v_cndmask_b32_e64 v198, v197, v198, s[56:57]
	v_fma_f32 v197, -v199, v197, v196
	v_cmp_lt_f32_e64 s[56:57], 0, v197
	s_nop 1
	v_cndmask_b32_e64 v197, v198, v199, s[56:57]
	v_mul_f32_e32 v198, 0x37800000, v197
	v_cndmask_b32_e32 v197, v197, v198, vcc
	v_mov_b32_e32 v198, 0x260
	v_cmp_class_f32_e32 vcc, v196, v198
	s_nop 1
	v_cndmask_b32_e32 v196, v197, v196, vcc
	v_max_f32_e32 v196, 0x2b8cbccc, v196
	v_div_scale_f32 v197, s[56:57], v196, v196, 1.0
	v_rcp_f32_e32 v198, v197
	s_nop 0
	v_fma_f32 v199, -v197, v198, 1.0
	v_fmac_f32_e32 v198, v199, v198
	v_div_scale_f32 v199, vcc, 1.0, v196, 1.0
	v_mul_f32_e32 v200, v199, v198
	v_fma_f32 v201, -v197, v200, v199
	v_fmac_f32_e32 v200, v201, v198
	v_fma_f32 v197, -v197, v200, v199
	s_nop 0
	v_div_fmas_f32 v197, v197, v198, v200
	v_div_fixup_f32 v232, v197, v196, 1.0
	v_pk_mul_f32 v[136:137], v[136:137], v[122:123]
	v_pk_mul_f32 v[138:139], v[138:139], v[122:123]
	v_pk_mul_f32 v[144:145], v[144:145], v[122:123]
	v_pk_mul_f32 v[146:147], v[146:147], v[122:123]
	v_pk_mul_f32 v[140:141], v[140:141], v[122:123]
	v_pk_mul_f32 v[142:143], v[142:143], v[122:123]
	v_pk_mul_f32 v[148:149], v[148:149], v[122:123]
	v_pk_mul_f32 v[150:151], v[150:151], v[122:123]
	v_exp_f32_e32 v136, v136
	v_exp_f32_e32 v137, v137
	v_exp_f32_e32 v138, v138
	v_exp_f32_e32 v139, v139
	v_exp_f32_e32 v144, v144
	v_exp_f32_e32 v145, v145
	v_exp_f32_e32 v146, v146
	v_exp_f32_e32 v147, v147
	v_exp_f32_e32 v140, v140
	v_exp_f32_e32 v141, v141
	v_exp_f32_e32 v142, v142
	v_exp_f32_e32 v143, v143
	v_exp_f32_e32 v148, v148
	v_exp_f32_e32 v149, v149
	v_exp_f32_e32 v150, v150
	v_exp_f32_e32 v151, v151
	v_pk_add_f32 v[136:137], v[136:137], 1.0 op_sel_hi:[1,0]
	v_pk_add_f32 v[138:139], v[138:139], 1.0 op_sel_hi:[1,0]
	v_pk_add_f32 v[144:145], v[144:145], 1.0 op_sel_hi:[1,0]
	v_pk_add_f32 v[146:147], v[146:147], 1.0 op_sel_hi:[1,0]
	v_pk_add_f32 v[140:141], v[140:141], 1.0 op_sel_hi:[1,0]
	v_pk_add_f32 v[142:143], v[142:143], 1.0 op_sel_hi:[1,0]
	v_pk_add_f32 v[148:149], v[148:149], 1.0 op_sel_hi:[1,0]
	v_pk_add_f32 v[150:151], v[150:151], 1.0 op_sel_hi:[1,0]
	v_rcp_f32_e32 v136, v136
	v_rcp_f32_e32 v137, v137
	v_rcp_f32_e32 v138, v138
	v_rcp_f32_e32 v139, v139
	v_rcp_f32_e32 v144, v144
	v_rcp_f32_e32 v145, v145
	v_rcp_f32_e32 v146, v146
	v_rcp_f32_e32 v147, v147
	v_rcp_f32_e32 v140, v140
	v_rcp_f32_e32 v141, v141
	v_rcp_f32_e32 v142, v142
	v_rcp_f32_e32 v143, v143
	v_rcp_f32_e32 v148, v148
	v_rcp_f32_e32 v149, v149
	v_rcp_f32_e32 v150, v150
	v_rcp_f32_e32 v151, v151
	v_pk_mul_f32 v[236:237], v[136:137], v[124:125]
	v_pk_mul_f32 v[238:239], v[138:139], v[124:125]
	v_pk_mul_f32 v[240:241], v[140:141], v[124:125]
	v_pk_mul_f32 v[242:243], v[142:143], v[124:125]
	v_pk_mul_f32 v[136:137], v[136:137], v[124:125]
	v_pk_mul_f32 v[138:139], v[138:139], v[124:125]
	v_pk_mul_f32 v[140:141], v[140:141], v[124:125]
	v_pk_mul_f32 v[142:143], v[142:143], v[124:125]
	v_add_f32_dpp v136, v136, v136 row_shr:1 row_mask:0xf bank_mask:0xf
	v_add_f32_dpp v137, v137, v137 row_shr:1 row_mask:0xf bank_mask:0xf
	v_add_f32_dpp v138, v138, v138 row_shr:1 row_mask:0xf bank_mask:0xf
	v_add_f32_dpp v139, v139, v139 row_shr:1 row_mask:0xf bank_mask:0xf
	v_add_f32_dpp v140, v140, v140 row_shr:1 row_mask:0xf bank_mask:0xf
	v_add_f32_dpp v141, v141, v141 row_shr:1 row_mask:0xf bank_mask:0xf
	v_add_f32_dpp v142, v142, v142 row_shr:1 row_mask:0xf bank_mask:0xf
	v_add_f32_dpp v143, v143, v143 row_shr:1 row_mask:0xf bank_mask:0xf
	v_add_f32_dpp v136, v136, v136 row_shr:2 row_mask:0xf bank_mask:0xf
	v_add_f32_dpp v137, v137, v137 row_shr:2 row_mask:0xf bank_mask:0xf
	v_add_f32_dpp v138, v138, v138 row_shr:2 row_mask:0xf bank_mask:0xf
	v_add_f32_dpp v139, v139, v139 row_shr:2 row_mask:0xf bank_mask:0xf
	v_add_f32_dpp v140, v140, v140 row_shr:2 row_mask:0xf bank_mask:0xf
	v_add_f32_dpp v141, v141, v141 row_shr:2 row_mask:0xf bank_mask:0xf
	v_add_f32_dpp v142, v142, v142 row_shr:2 row_mask:0xf bank_mask:0xf
	v_add_f32_dpp v143, v143, v143 row_shr:2 row_mask:0xf bank_mask:0xf
	v_add_f32_dpp v136, v136, v136 row_shr:4 row_mask:0xf bank_mask:0xf
	v_add_f32_dpp v137, v137, v137 row_shr:4 row_mask:0xf bank_mask:0xf
	v_add_f32_dpp v138, v138, v138 row_shr:4 row_mask:0xf bank_mask:0xf
	v_add_f32_dpp v139, v139, v139 row_shr:4 row_mask:0xf bank_mask:0xf
; __device__ __forceinline__ void phase_rwkv_scan(const Fr& F, int jr) {
;     ...
;                 if (s == 0 && half == 0 && j8 == 0) Bon[((size_t)b * TB + tokof(s, chunk * 64 + p2)) * 16 + h] = bon;
;                 const float inv = 1.f / fmaxf(sqrtf(ss), 1e-12f);
;                 const f32x4 av0 = *(const f32x4*)(Av + p2 * 64 + hk0), av1 = *(const f32x4*)(Av + p2 * 64 + hk0 + 4);
;                 const float av[8] = {av0.x, av0.y, av0.z, av0.w, av1.x, av1.y, av1.z, av1.w};
;                 float o1[8], o2[8], o3[8];
; #pragma unroll
;                 for (int i = 0; i < 8; ++i) { const float kkv = kq[i] * inv; o1[i] = kkv; o2[i] = kkv * av[i]; o3[i] = kr[i] * (1.f + (av[i] - 1.f) * kac[i]); }
;                 const int o = p2 * 64 + hk0;
;                 *(f32x4*)(KK + o) = (f32x4){o1[0], o1[1], o1[2], o1[3]}; *(f32x4*)(KK + o + 4) = (f32x4){o1[4], o1[5], o1[6], o1[7]};
;                 *(f32x4*)(Bv + o) = (f32x4){o2[0], o2[1], o2[2], o2[3]}; *(f32x4*)(Bv + o + 4) = (f32x4){o2[4], o2[5], o2[6], o2[7]};
;                 *(f32x4*)(KD + o) = (f32x4){o3[0], o3[1], o3[2], o3[3]}; *(f32x4*)(KD + o + 4) = (f32x4){o3[4], o3[5], o3[6], o3[7]};
;                 *(f32x4*)(Rr + o) = (f32x4){rr[0], rr[1], rr[2], rr[3]}; *(f32x4*)(Rr + o + 4) = (f32x4){rr[4], rr[5], rr[6], rr[7]};
;                 *(f32x4*)(Vv + p2 * 32 + 4 * j8) = (f32x4){lo_bf(vw.x), hi_bf(vw.x), lo_bf(vw.y), hi_bf(vw.y)};
	v_add_f32_dpp v140, v140, v140 row_shr:4 row_mask:0xf bank_mask:0xf
	v_add_f32_dpp v141, v141, v141 row_shr:4 row_mask:0xf bank_mask:0xf
	v_add_f32_dpp v142, v142, v142 row_shr:4 row_mask:0xf bank_mask:0xf
	v_add_f32_dpp v143, v143, v143 row_shr:4 row_mask:0xf bank_mask:0xf
	v_add_f32_dpp v136, v136, v136 row_shr:8 row_mask:0xf bank_mask:0xf
	v_add_f32_dpp v137, v137, v137 row_shr:8 row_mask:0xf bank_mask:0xf
	v_add_f32_dpp v138, v138, v138 row_shr:8 row_mask:0xf bank_mask:0xf
	v_add_f32_dpp v139, v139, v139 row_shr:8 row_mask:0xf bank_mask:0xf
	v_add_f32_dpp v140, v140, v140 row_shr:8 row_mask:0xf bank_mask:0xf
	v_add_f32_dpp v141, v141, v141 row_shr:8 row_mask:0xf bank_mask:0xf
	v_add_f32_dpp v142, v142, v142 row_shr:8 row_mask:0xf bank_mask:0xf
	v_add_f32_dpp v143, v143, v143 row_shr:8 row_mask:0xf bank_mask:0xf
	v_pk_add_f32 v[236:237], v[136:137], v[236:237] neg_lo:[0,1] neg_hi:[0,1]
	v_pk_add_f32 v[238:239], v[138:139], v[238:239] neg_lo:[0,1] neg_hi:[0,1]
	v_pk_add_f32 v[240:241], v[140:141], v[240:241] neg_lo:[0,1] neg_hi:[0,1]
	v_pk_add_f32 v[242:243], v[142:143], v[242:243] neg_lo:[0,1] neg_hi:[0,1]
	v_exp_f32_e64 v244, -v136
	v_exp_f32_e64 v245, -v137
	v_exp_f32_e64 v246, -v138
	v_exp_f32_e64 v247, -v139
	v_exp_f32_e64 v248, -v140
	v_exp_f32_e64 v249, -v141
	v_exp_f32_e64 v250, -v142
	v_exp_f32_e64 v251, -v143
	v_exp_f32_e32 v236, v236
	v_exp_f32_e32 v237, v237
	v_exp_f32_e32 v238, v238
	v_exp_f32_e32 v239, v239
	v_exp_f32_e32 v240, v240
	v_exp_f32_e32 v241, v241
	v_exp_f32_e32 v242, v242
	v_exp_f32_e32 v243, v243
	v_exp_f32_e32 v136, v136
	v_exp_f32_e32 v137, v137
	v_exp_f32_e32 v138, v138
	v_exp_f32_e32 v139, v139
	v_exp_f32_e32 v140, v140
	v_exp_f32_e32 v141, v141
	v_exp_f32_e32 v142, v142
	v_exp_f32_e32 v143, v143
	v_pk_mul_f32 v[204:205], v[176:177], v[232:233] op_sel_hi:[1,0]
	v_pk_mul_f32 v[206:207], v[178:179], v[232:233] op_sel_hi:[1,0]
	v_pk_add_f32 v[212:213], v[144:145], -1.0 op_sel_hi:[1,0]
	v_pk_add_f32 v[214:215], v[146:147], -1.0 op_sel_hi:[1,0]
	v_pk_mul_f32 v[208:209], v[204:205], v[144:145]
	v_pk_mul_f32 v[210:211], v[206:207], v[146:147]
	v_pk_fma_f32 v[212:213], v[64:65], v[212:213], 1.0 op_sel_hi:[1,1,0]
	v_pk_fma_f32 v[214:215], v[66:67], v[214:215], 1.0 op_sel_hi:[1,1,0]
	ds_write_b128 v224, v[136:139] offset:0
	v_pk_mul_f32 v[204:205], v[204:205], v[236:237]
	v_pk_mul_f32 v[206:207], v[206:207], v[238:239]
	v_pk_mul_f32 v[212:213], v[212:213], v[152:153]
	v_pk_mul_f32 v[214:215], v[214:215], v[154:155]
	ds_write_b128 v224, v[204:207] offset:8704
	v_pk_mul_f32 v[208:209], v[208:209], v[244:245]
	v_pk_mul_f32 v[210:211], v[210:211], v[246:247]
	v_pk_mul_f32 v[196:197], v[168:169], v[136:137]
	v_pk_mul_f32 v[198:199], v[170:171], v[138:139]
	ds_write_b128 v224, v[208:211] offset:17408
	v_pk_mul_f32 v[212:213], v[212:213], v[244:245]
	v_pk_mul_f32 v[214:215], v[214:215], v[246:247]
	ds_write_b128 v224, v[196:199] offset:34816
	ds_write_b128 v224, v[212:215] offset:26112
	v_pk_mul_f32 v[204:205], v[180:181], v[232:233] op_sel_hi:[1,0]
	v_pk_mul_f32 v[206:207], v[182:183], v[232:233] op_sel_hi:[1,0]
	v_pk_add_f32 v[212:213], v[148:149], -1.0 op_sel_hi:[1,0]
	v_pk_add_f32 v[214:215], v[150:151], -1.0 op_sel_hi:[1,0]
	v_pk_mul_f32 v[208:209], v[204:205], v[148:149]
	v_pk_mul_f32 v[210:211], v[206:207], v[150:151]
	v_pk_fma_f32 v[212:213], v[68:69], v[212:213], 1.0 op_sel_hi:[1,1,0]
	v_pk_fma_f32 v[214:215], v[70:71], v[214:215], 1.0 op_sel_hi:[1,1,0]
	ds_write_b128 v224, v[140:143] offset:64
	v_pk_mul_f32 v[204:205], v[204:205], v[240:241]
	v_pk_mul_f32 v[206:207], v[206:207], v[242:243]
	v_pk_mul_f32 v[212:213], v[212:213], v[156:157]
	v_pk_mul_f32 v[214:215], v[214:215], v[158:159]
	ds_write_b128 v224, v[204:207] offset:8768
	v_pk_mul_f32 v[208:209], v[208:209], v[248:249]
	v_pk_mul_f32 v[210:211], v[210:211], v[250:251]
	v_pk_mul_f32 v[196:197], v[172:173], v[140:141]
	v_pk_mul_f32 v[198:199], v[174:175], v[142:143]
	ds_write_b128 v224, v[208:211] offset:17472
	v_pk_mul_f32 v[212:213], v[212:213], v[248:249]
	v_pk_mul_f32 v[214:215], v[214:215], v[250:251]
	ds_write_b128 v224, v[196:199] offset:34880
	ds_write_b128 v224, v[212:215] offset:26176
	v_mov_b32_e32 v204, v193
	v_mov_b32_e32 v205, v192
	v_mov_b32_e32 v206, v195
	v_mov_b32_e32 v207, v194
	ds_write_b64 v225, v[192:193] offset:43520
	ds_write_b64 v225, v[204:205] offset:43536
	ds_write_b64 v225, v[194:195] offset:43552
	ds_write_b64 v225, v[206:207] offset:43568
	s_cmp_eq_u32 s32, 0
	s_cbranch_scc1 .Lrw0_hnb0
	v_mov_b32_e32 v196, v234
	s_nop 1
	v_permlane16_swap_b32_e32 v234, v196
	s_nop 1
	v_add_f32_e32 v234, v234, v196
	v_mov_b32_e32 v196, v234
	s_nop 1
	v_permlane32_swap_b32_e32 v234, v196
	s_nop 1
	v_add_f32_e32 v234, v234, v196
	v_cmp_gt_u32_e32 vcc, 16, v130
	s_and_saveexec_b64 s[56:57], vcc
	global_store_dword v202, v234, s[44:45]
	s_mov_b64 exec, s[56:57]

; __device__ __forceinline__ float sigm(float x) { return __builtin_amdgcn_rcpf(1.f + __expf(-x)); }
; #define LDS_BAR() asm volatile("s_waitcnt lgkmcnt(0)\n\ts_barrier" ::: "memory")
; __device__ __forceinline__ void phase_rwkv_scan(const Fr& F, int jr) {
;     ...
;         for (int chunk = 0; chunk < TB / 64; ++chunk) {
; #pragma unroll
;             for (int hh = 0; hh < 2; ++hh) {
;                 const int hk = (ht0 + hh) * 16 + l15;
;                 f32x4 cw = {0.f, 0.f, 0.f, 0.f}, ca = {0.f, 0.f, 0.f, 0.f};
; #pragma unroll
;                 for (int kst = 0; kst < 2; ++kst) { cw = __builtin_amdgcn_mfma_f32_16x16x32_bf16(Aw[kst], Bw[hh][kst], cw, 0, 0, 0); ca = __builtin_amdgcn_mfma_f32_16x16x32_bf16(Aa[kst], Ba[hh][kst], ca, 0, 0, 0); }
; #pragma unroll
;                 for (int reg = 0; reg < 4; ++reg) { const int pp = pt * 16 + lq * 4 + reg;
;                     Wv[pp * 64 + hk] = __expf(-0.60653066f * sigm(w0v[hh] + cw[reg]));
;                     Av[pp * 64 + hk] = sigm(a0v[hh] + ca[reg]); }
;             }
;             LDS_BAR();
;             {
;                 const float kr[8] = {lo_bf(kw.x), hi_bf(kw.x), lo_bf(kw.y), hi_bf(kw.y), lo_bf(kw.z), hi_bf(kw.z), lo_bf(kw.w), hi_bf(kw.w)};
;                 const float rr[8] = {lo_bf(rw.x), hi_bf(rw.x), lo_bf(rw.y), hi_bf(rw.y), lo_bf(rw.z), hi_bf(rw.z), lo_bf(rw.w), hi_bf(rw.w)};
;                 float kq[8]; float ss = 0.f, bon = 0.f;
; #pragma unroll
;                 for (int i = 0; i < 8; ++i) { kq[i] = kr[i] * kkc[i]; ss += kq[i] * kq[i]; bon += rr[i] * kr[i] * rkc[i]; }
.Lrw0_hhc:
	s_cmp_lt_u32 s10, 136
	s_cbranch_scc0 .Lrw0_hlast
	s_xor_b32 s11, s11, 0xcc00
	v_add_u32_e32 v224, s11, v222
	v_add_u32_e32 v225, s11, v223
	v_mov_b32_e32 v202, v230
	s_and_b32 s17, s10, 3
	s_cmp_eq_u32 s17, s59
	s_cselect_b32 s32, s58, 0
	s_waitcnt vmcnt(0)
	v_mfma_f32_16x16x32_bf16 v[136:139], v[0:3], v[88:91], v[32:35]
	v_mfma_f32_16x16x32_bf16 v[136:139], v[4:7], v[92:95], v[136:139]
	v_mfma_f32_16x16x32_bf16 v[140:143], v[8:11], v[88:91], v[36:39]
	v_mfma_f32_16x16x32_bf16 v[140:143], v[12:15], v[92:95], v[140:143]
	v_mfma_f32_16x16x32_bf16 v[144:147], v[16:19], v[96:99], v[40:43]
	v_mfma_f32_16x16x32_bf16 v[144:147], v[20:23], v[100:103], v[144:147]
	v_mfma_f32_16x16x32_bf16 v[148:151], v[24:27], v[96:99], v[44:47]
	v_mfma_f32_16x16x32_bf16 v[148:151], v[28:31], v[100:103], v[148:151]
	v_lshlrev_b32_e32 v152, 16, v104
	v_and_b32_e32 v153, 0xffff0000, v104
	v_lshlrev_b32_e32 v154, 16, v105
	v_and_b32_e32 v155, 0xffff0000, v105
	v_lshlrev_b32_e32 v156, 16, v106
	v_and_b32_e32 v157, 0xffff0000, v106
	v_lshlrev_b32_e32 v158, 16, v107
	v_and_b32_e32 v159, 0xffff0000, v107
	v_lshlrev_b32_e32 v160, 16, v108
	v_and_b32_e32 v161, 0xffff0000, v108
	v_lshlrev_b32_e32 v162, 16, v109
	v_and_b32_e32 v163, 0xffff0000, v109
	v_lshlrev_b32_e32 v164, 16, v110
	v_and_b32_e32 v165, 0xffff0000, v110
	v_lshlrev_b32_e32 v166, 16, v111
	v_and_b32_e32 v167, 0xffff0000, v111
	v_lshlrev_b32_e32 v168, 16, v112
	v_and_b32_e32 v169, 0xffff0000, v112
	v_lshlrev_b32_e32 v170, 16, v113
	v_and_b32_e32 v171, 0xffff0000, v113
	v_lshlrev_b32_e32 v172, 16, v114
	v_and_b32_e32 v173, 0xffff0000, v114
	v_lshlrev_b32_e32 v174, 16, v115
	v_and_b32_e32 v175, 0xffff0000, v115
	v_lshlrev_b32_e32 v192, 16, v120
	v_and_b32_e32 v193, 0xffff0000, v120
	v_lshlrev_b32_e32 v194, 16, v121
	v_and_b32_e32 v195, 0xffff0000, v121
	v_pk_mul_f32 v[176:177], v[152:153], v[48:49]
	v_pk_mul_f32 v[178:179], v[154:155], v[50:51]
	v_pk_mul_f32 v[180:181], v[156:157], v[52:53]
	v_pk_mul_f32 v[182:183], v[158:159], v[54:55]
	v_pk_mul_f32 v[184:185], v[160:161], v[56:57]
	v_pk_mul_f32 v[186:187], v[162:163], v[58:59]
	v_pk_mul_f32 v[188:189], v[164:165], v[60:61]
	v_pk_mul_f32 v[190:191], v[166:167], v[62:63]
	v_pk_mul_f32 v[196:197], v[176:177], v[176:177]
	v_pk_mul_f32 v[198:199], v[178:179], v[178:179]
	v_pk_fma_f32 v[196:197], v[180:181], v[180:181], v[196:197]
	v_pk_fma_f32 v[198:199], v[182:183], v[182:183], v[198:199]
	v_pk_fma_f32 v[196:197], v[184:185], v[184:185], v[196:197]
	v_pk_fma_f32 v[198:199], v[186:187], v[186:187], v[198:199]
	v_pk_fma_f32 v[196:197], v[188:189], v[188:189], v[196:197]
	v_pk_fma_f32 v[198:199], v[190:191], v[190:191], v[198:199]
	s_nop 0
	v_pk_add_f32 v[196:197], v[196:197], v[198:199]
	s_cmp_eq_u32 s32, 0
	s_cbranch_scc1 .Lrw0_hnbc1
	v_mul_f32_e32 v208, v168, v152
	v_mul_f32_e32 v209, v169, v153
	v_mul_f32_e32 v210, v170, v154
	v_mul_f32_e32 v211, v171, v155
	v_mul_f32_e32 v234, v72, v208
	v_fmac_f32_e32 v234, v73, v209
	v_fmac_f32_e32 v234, v74, v210
	v_fmac_f32_e32 v234, v75, v211
	v_mul_f32_e32 v208, v172, v156
	v_mul_f32_e32 v209, v173, v157
	v_mul_f32_e32 v210, v174, v158
	v_mul_f32_e32 v211, v175, v159
	v_fmac_f32_e32 v234, v76, v208
	v_fmac_f32_e32 v234, v77, v209
	v_fmac_f32_e32 v234, v78, v210
	v_fmac_f32_e32 v234, v79, v211
	v_lshlrev_b32_e32 v204, 16, v116
	v_and_b32_e32 v205, 0xffff0000, v116
	v_lshlrev_b32_e32 v206, 16, v117
	v_and_b32_e32 v207, 0xffff0000, v117
	v_mul_f32_e32 v208, v204, v160
	v_mul_f32_e32 v209, v205, v161
	v_mul_f32_e32 v210, v206, v162
	v_mul_f32_e32 v211, v207, v163
	v_fmac_f32_e32 v234, v80, v208
	v_fmac_f32_e32 v234, v81, v209
	v_fmac_f32_e32 v234, v82, v210
	v_fmac_f32_e32 v234, v83, v211
	v_lshlrev_b32_e32 v204, 16, v118
	v_and_b32_e32 v205, 0xffff0000, v118
	v_lshlrev_b32_e32 v206, 16, v119
	v_and_b32_e32 v207, 0xffff0000, v119
	v_mul_f32_e32 v208, v204, v164
	v_mul_f32_e32 v209, v205, v165
	v_mul_f32_e32 v210, v206, v166
	v_mul_f32_e32 v211, v207, v167
	v_fmac_f32_e32 v234, v84, v208
	v_fmac_f32_e32 v234, v85, v209
	v_fmac_f32_e32 v234, v86, v210
	v_fmac_f32_e32 v234, v87, v211

;     __device__ __forceinline__ bf16* R(int i) const { return (bf16*)(ws + OFF_R0 + (size_t)i * RSZ); }
; __device__ __forceinline__ void phase_rwkv_scan(const Fr& F, int jr) {
;     ...
;         const int half = task & 1, h = (task >> 1) & 15, b = (task >> 5) & 3, s = task >> 7;
;         bf16* Yb = F.R(s);
;         const float* w0 = F.a->in[9] + (size_t)(jr * 2 + s) * D + h * 64; const float* a0 = F.a->in[12] + (size_t)(jr * 2 + s) * D + h * 64;
;         const float* kkw = F.a->in[15] + (size_t)jr * D + h * 64; const float* kaw = F.a->in[16] + (size_t)jr * D + h * 64;
;         f32x2 S01 = {0.f, 0.f}, S23 = {0.f, 0.f};
;         const int ks = 4 * l15, rloc = 4 * wave + lq;
;         const int pt = wave & 3, ht0 = (wave >> 2) * 2;
;         const int p1 = pt * 16 + l15;
;         const int p2 = tid >> 3, j8 = tid & 7, hk0 = 8 * j8;
;         bf16x8 Bw[2][2], Ba[2][2]; float w0v[2], a0v[2];
; #pragma unroll
;         for (int hh = 0; hh < 2; ++hh) { const int hk = (ht0 + hh) * 16 + l15, e = h * 64 + hk; w0v[hh] = w0[hk]; a0v[hh] = a0[hk];
; #pragma unroll
;             for (int kst = 0; kst < 2; ++kst) { Bw[hh][kst] = *(const bf16x8*)(L2T + ((size_t)s * D + e) * 64 + 32 * kst + 8 * lq); Ba[hh][kst] = *(const bf16x8*)(L2T + ((size_t)(2 + s) * D + e) * 64 + 32 * kst + 8 * lq); } }
;         float kkc[8], kac[8], rkc[8];
; #pragma unroll
;         for (int i = 0; i < 8; ++i) { kkc[i] = kkw[hk0 + i]; kac[i] = kaw[hk0 + i]; rkc[i] = F.a->in[17][(size_t)jr * D + h * 64 + hk0 + i]; }
;         float* Bon = (float*)(F.ws + OFF_R0 + 6 * RSZ + 16 * MiB);
;         bf16x8 Aw[2], Aa[2]; u32x4 kw, rw; u32x2 vw;
;         {   const size_t row1 = (size_t)b * TB + tokof(s, p1), row2 = (size_t)b * TB + tokof(s, p2);
; #pragma unroll
;             for (int kst = 0; kst < 2; ++kst) { Aw[kst] = *(const bf16x8*)(LM + row1 * 256 + 64 * s + 32 * kst + 8 * lq); Aa[kst] = *(const bf16x8*)(LM + row1 * 256 + 128 + 64 * s + 32 * kst + 8 * lq); }
;             kw = *(const u32x4*)(Kb + row2 * D + h * 64 + hk0); rw = *(const u32x4*)(Rb + row2 * D + h * 64 + hk0); vw = *(const u32x2*)(Vb + row2 * D + h * 64 + 32 * half + 4 * j8); }
.Lrw3_hdir0:
	s_mul_i32 s16, s7, 0x1100
	v_lshlrev_b32_e32 v221, 4, v217
	s_lshl_b32 s17, s15, 6
	v_lshl_add_u32 v219, v217, 3, s17
	s_xor_b32 s18, s17, 64
	v_lshl_add_u32 v220, v217, 3, s18
	s_lshl_b32 s17, s15, 7
	v_mul_u32_u24_e32 v197, 0x110, v216
	v_add_u32_e32 v197, s17, v197
	v_lshl_add_u32 v222, v217, 4, v197
	v_lshrrev_b32_e32 v201, 1, v216
	v_mul_u32_u24_e32 v201, 0x210, v201
	v_and_b32_e32 v203, 1, v216
	v_lshl_add_u32 v201, v203, 3, v201
	s_lshl_b32 s18, s15, 8
	v_lshl_add_u32 v203, v217, 6, s18
	v_add_u32_e32 v223, v201, v203
	s_lshl_b32 s17, s6, 7
	s_add_u32 s20, s26, 0xde00000
	s_addc_u32 s21, s27, 0
	s_add_u32 s20, s20, s17
	s_addc_u32 s21, s21, 0
	s_lshl_b32 s17, s8, 7
	s_add_u32 s22, s26, 0xbc00000
	s_addc_u32 s23, s27, 0
	s_add_u32 s22, s22, s17
	s_addc_u32 s23, s23, 0
	s_add_u32 s24, s26, 0x9a00000
	s_addc_u32 s25, s27, 0
	s_add_u32 s24, s24, s17
	s_addc_u32 s25, s25, 0
	s_lshl_b32 s18, s9, 6
	s_add_i32 s17, s17, s18
	s_lshl_b32 s18, s15, 5
	s_add_i32 s17, s17, s18
	s_add_u32 s42, s26, 0x5600000
	s_addc_u32 s43, s27, 0
	s_add_u32 s42, s42, s17
	s_addc_u32 s43, s43, 0
	s_lshl_b32 s17, s8, 2
	s_add_u32 s44, s26, 0xee00000
	s_addc_u32 s45, s27, 0
	s_add_u32 s44, s44, s17
	s_addc_u32 s45, s45, 0
	s_cmp_eq_u32 s15, 0
	s_cselect_b32 s58, 1, 0
	s_xor_b32 s59, s6, s9
	s_load_dwordx2 s[46:47], s[0:1], 0x48
	s_load_dwordx2 s[48:49], s[0:1], 0x60
	s_load_dwordx2 s[50:51], s[0:1], 0x78
	s_load_dwordx2 s[52:53], s[0:1], 0x80
	s_load_dwordx2 s[54:55], s[0:1], 0x88
	s_lshl_b32 s17, s8, 8
	s_lshl_b32 s18, s15, 7
	s_add_i32 s19, s17, s18
	v_lshl_add_u32 v198, v217, 4, s19
	s_xor_b32 s18, s18, 128
	s_add_i32 s19, s17, s18
	v_lshl_add_u32 v199, v217, 4, s19
	s_waitcnt lgkmcnt(0)
	s_lshl_b32 s17, s6, 12
	s_add_u32 s46, s46, s17
	s_addc_u32 s47, s47, 0
	s_add_u32 s48, s48, s17
	s_addc_u32 s49, s49, 0
	s_add_u32 s46, s46, 0x2000
	s_addc_u32 s47, s47, 0
	s_add_u32 s48, s48, 0x2000
	s_addc_u32 s49, s49, 0
	s_add_u32 s50, s50, 0x1000
	s_addc_u32 s51, s51, 0
	s_add_u32 s52, s52, 0x1000
	s_addc_u32 s53, s53, 0
	s_add_u32 s54, s54, 0x1000
	s_addc_u32 s55, s55, 0
	global_load_dwordx4 v[32:35], v198, s[46:47] offset:0
	global_load_dwordx4 v[40:43], v198, s[48:49] offset:0
	global_load_dwordx4 v[64:67], v198, s[52:53] offset:0
	global_load_dwordx4 v[36:39], v198, s[46:47] offset:64
	global_load_dwordx4 v[44:47], v198, s[48:49] offset:64
	global_load_dwordx4 v[68:71], v198, s[52:53] offset:64
	global_load_dwordx4 v[48:51], v198, s[50:51] offset:0
	global_load_dwordx4 v[72:75], v198, s[54:55] offset:0
	global_load_dwordx4 v[52:55], v198, s[50:51] offset:64
	global_load_dwordx4 v[76:79], v198, s[54:55] offset:64
	global_load_dwordx4 v[56:59], v199, s[50:51] offset:0
	global_load_dwordx4 v[80:83], v199, s[54:55] offset:0
	global_load_dwordx4 v[60:63], v199, s[50:51] offset:64
	global_load_dwordx4 v[84:87], v199, s[54:55] offset:64
	s_lshl_b32 s17, s8, 6
	s_lshl_b32 s18, s15, 5
	s_add_i32 s17, s17, s18
	v_add_u32_e32 v200, s17, v196
	v_lshlrev_b32_e32 v200, 7, v200
	v_add_u32_e32 v200, v200, v221
	s_lshl_b32 s17, s6, 17
	s_add_u32 s46, s26, 0x200000
	s_addc_u32 s47, s27, 0
	s_add_u32 s46, s46, s17
	s_addc_u32 s47, s47, 0
	s_add_u32 s48, s46, 0x40000
	s_addc_u32 s49, s47, 0
	global_load_dwordx4 v[0:3], v200, s[46:47] offset:0
	global_load_dwordx4 v[16:19], v200, s[48:49] offset:0
	global_load_dwordx4 v[4:7], v200, s[46:47] offset:64
	global_load_dwordx4 v[20:23], v200, s[48:49] offset:64
	global_load_dwordx4 v[8:11], v200, s[46:47] offset:2048
	global_load_dwordx4 v[24:27], v200, s[48:49] offset:2048
	global_load_dwordx4 v[12:15], v200, s[46:47] offset:2112
	global_load_dwordx4 v[28:31], v200, s[48:49] offset:2112
	s_mov_b32 s10, 0
	s_mov_b32 s11, 0
	s_lshl_b32 s17, s10, 5
	s_cmp_lt_u32 s10, 8
	s_movk_i32 s18, 0x11ff
	s_cselect_b32 s18, 0xff, s18
	s_sub_i32 s18, s18, s17
	s_cmp_eq_u32 s6, 0
	s_cselect_b32 s17, s17, s18
	s_add_i32 s17, s17, s16
	v_add_u32_e32 v231, s17, v218
	v_lshl_add_u32 v226, v231, 9, v221
	v_lshl_add_u32 v227, v231, 11, v219
	v_lshl_add_u32 v228, v231, 11, v220
	v_lshlrev_b32_e32 v229, 3, v217
	v_lshl_add_u32 v229, v231, 11, v229
	v_lshlrev_b32_e32 v230, 6, v231
	global_load_dwordx4 v[88:91], v226, s[20:21]
	global_load_dwordx4 v[92:95], v226, s[20:21] offset:64
	global_load_dwordx4 v[96:99], v226, s[20:21] offset:256
	global_load_dwordx4 v[100:103], v226, s[20:21] offset:320
	global_load_dwordx2 v[104:105], v227, s[22:23] offset:0
	global_load_dwordx2 v[106:107], v227, s[22:23] offset:32
	global_load_dwordx2 v[108:109], v228, s[22:23] offset:0
	global_load_dwordx2 v[110:111], v228, s[22:23] offset:32
	global_load_dwordx2 v[112:113], v227, s[24:25] offset:0
	global_load_dwordx2 v[114:115], v227, s[24:25] offset:32
	global_load_dwordx2 v[116:117], v228, s[24:25] offset:0
	global_load_dwordx2 v[118:119], v228, s[24:25] offset:32
	global_load_dwordx2 v[120:121], v229, s[42:43]
	v_mov_b32_e32 v224, v222
	v_mov_b32_e32 v225, v223
	v_mov_b32_e32 v202, v230
	s_and_b32 s17, s10, 3
	s_cmp_eq_u32 s17, s59
	s_cselect_b32 s32, s58, 0
	s_waitcnt vmcnt(0)
; __device__ __forceinline__ float sigm(float x) { return __builtin_amdgcn_rcpf(1.f + __expf(-x)); }
; #define LDS_BAR() asm volatile("s_waitcnt lgkmcnt(0)\n\ts_barrier" ::: "memory")
; __device__ __forceinline__ void phase_rwkv_scan(const Fr& F, int jr) {
;     ...
;                 for (int kst = 0; kst < 2; ++kst) { cw = __builtin_amdgcn_mfma_f32_16x16x32_bf16(Aw[kst], Bw[hh][kst], cw, 0, 0, 0); ca = __builtin_amdgcn_mfma_f32_16x16x32_bf16(Aa[kst], Ba[hh][kst], ca, 0, 0, 0); }
; #pragma unroll
;                 for (int reg = 0; reg < 4; ++reg) { const int pp = pt * 16 + lq * 4 + reg;
;                     Wv[pp * 64 + hk] = __expf(-0.60653066f * sigm(w0v[hh] + cw[reg]));
;                     Av[pp * 64 + hk] = sigm(a0v[hh] + ca[reg]); }
;             }
;             LDS_BAR();
;             {
;                 const float kr[8] = {lo_bf(kw.x), hi_bf(kw.x), lo_bf(kw.y), hi_bf(kw.y), lo_bf(kw.z), hi_bf(kw.z), lo_bf(kw.w), hi_bf(kw.w)};
;                 const float rr[8] = {lo_bf(rw.x), hi_bf(rw.x), lo_bf(rw.y), hi_bf(rw.y), lo_bf(rw.z), hi_bf(rw.z), lo_bf(rw.w), hi_bf(rw.w)};
;                 float kq[8]; float ss = 0.f, bon = 0.f;
; #pragma unroll
;                 for (int i = 0; i < 8; ++i) { kq[i] = kr[i] * kkc[i]; ss += kq[i] * kq[i]; bon += rr[i] * kr[i] * rkc[i]; }
	v_mfma_f32_16x16x32_bf16 v[136:139], v[0:3], v[88:91], v[32:35]
	v_mfma_f32_16x16x32_bf16 v[136:139], v[4:7], v[92:95], v[136:139]
	v_mfma_f32_16x16x32_bf16 v[140:143], v[8:11], v[88:91], v[36:39]
	v_mfma_f32_16x16x32_bf16 v[140:143], v[12:15], v[92:95], v[140:143]
	v_mfma_f32_16x16x32_bf16 v[144:147], v[16:19], v[96:99], v[40:43]
	v_mfma_f32_16x16x32_bf16 v[144:147], v[20:23], v[100:103], v[144:147]
	v_mfma_f32_16x16x32_bf16 v[148:151], v[24:27], v[96:99], v[44:47]
	v_mfma_f32_16x16x32_bf16 v[148:151], v[28:31], v[100:103], v[148:151]
	v_lshlrev_b32_e32 v152, 16, v104
	v_and_b32_e32 v153, 0xffff0000, v104
	v_lshlrev_b32_e32 v154, 16, v105
	v_and_b32_e32 v155, 0xffff0000, v105
	v_lshlrev_b32_e32 v156, 16, v106
	v_and_b32_e32 v157, 0xffff0000, v106
	v_lshlrev_b32_e32 v158, 16, v107
	v_and_b32_e32 v159, 0xffff0000, v107
	v_lshlrev_b32_e32 v160, 16, v108
	v_and_b32_e32 v161, 0xffff0000, v108
	v_lshlrev_b32_e32 v162, 16, v109
	v_and_b32_e32 v163, 0xffff0000, v109
	v_lshlrev_b32_e32 v164, 16, v110
	v_and_b32_e32 v165, 0xffff0000, v110
	v_lshlrev_b32_e32 v166, 16, v111
	v_and_b32_e32 v167, 0xffff0000, v111
	v_lshlrev_b32_e32 v168, 16, v112
	v_and_b32_e32 v169, 0xffff0000, v112
	v_lshlrev_b32_e32 v170, 16, v113
	v_and_b32_e32 v171, 0xffff0000, v113
	v_lshlrev_b32_e32 v172, 16, v114
	v_and_b32_e32 v173, 0xffff0000, v114
	v_lshlrev_b32_e32 v174, 16, v115
	v_and_b32_e32 v175, 0xffff0000, v115
	v_lshlrev_b32_e32 v192, 16, v120
	v_and_b32_e32 v193, 0xffff0000, v120
	v_lshlrev_b32_e32 v194, 16, v121
	v_and_b32_e32 v195, 0xffff0000, v121
	v_pk_mul_f32 v[176:177], v[152:153], v[48:49]
	v_pk_mul_f32 v[178:179], v[154:155], v[50:51]
	v_pk_mul_f32 v[180:181], v[156:157], v[52:53]
	v_pk_mul_f32 v[182:183], v[158:159], v[54:55]
	v_pk_mul_f32 v[184:185], v[160:161], v[56:57]
	v_pk_mul_f32 v[186:187], v[162:163], v[58:59]
	v_pk_mul_f32 v[188:189], v[164:165], v[60:61]
	v_pk_mul_f32 v[190:191], v[166:167], v[62:63]
	v_pk_mul_f32 v[196:197], v[176:177], v[176:177]
	v_pk_mul_f32 v[198:199], v[178:179], v[178:179]
	v_pk_fma_f32 v[196:197], v[180:181], v[180:181], v[196:197]
	v_pk_fma_f32 v[198:199], v[182:183], v[182:183], v[198:199]
	v_pk_fma_f32 v[196:197], v[184:185], v[184:185], v[196:197]
	v_pk_fma_f32 v[198:199], v[186:187], v[186:187], v[198:199]
	v_pk_fma_f32 v[196:197], v[188:189], v[188:189], v[196:197]
	v_pk_fma_f32 v[198:199], v[190:191], v[190:191], v[198:199]
	s_nop 0
	v_pk_add_f32 v[196:197], v[196:197], v[198:199]
	s_cmp_eq_u32 s32, 0
	s_cbranch_scc1 .Lrw3_hnbc0
	v_mul_f32_e32 v208, v168, v152
	v_mul_f32_e32 v209, v169, v153
	v_mul_f32_e32 v210, v170, v154
	v_mul_f32_e32 v211, v171, v155
	v_mul_f32_e32 v234, v72, v208
	v_fmac_f32_e32 v234, v73, v209
	v_fmac_f32_e32 v234, v74, v210
	v_fmac_f32_e32 v234, v75, v211
	v_mul_f32_e32 v208, v172, v156
	v_mul_f32_e32 v209, v173, v157
	v_mul_f32_e32 v210, v174, v158
	v_mul_f32_e32 v211, v175, v159
	v_fmac_f32_e32 v234, v76, v208
	v_fmac_f32_e32 v234, v77, v209
	v_fmac_f32_e32 v234, v78, v210
	v_fmac_f32_e32 v234, v79, v211
	v_lshlrev_b32_e32 v204, 16, v116
	v_and_b32_e32 v205, 0xffff0000, v116
	v_lshlrev_b32_e32 v206, 16, v117
	v_and_b32_e32 v207, 0xffff0000, v117
	v_mul_f32_e32 v208, v204, v160
	v_mul_f32_e32 v209, v205, v161
	v_mul_f32_e32 v210, v206, v162
	v_mul_f32_e32 v211, v207, v163
	v_fmac_f32_e32 v234, v80, v208
	v_fmac_f32_e32 v234, v81, v209
	v_fmac_f32_e32 v234, v82, v210
	v_fmac_f32_e32 v234, v83, v211
	v_lshlrev_b32_e32 v204, 16, v118
	v_and_b32_e32 v205, 0xffff0000, v118
	v_lshlrev_b32_e32 v206, 16, v119
	v_and_b32_e32 v207, 0xffff0000, v119
	v_mul_f32_e32 v208, v204, v164
	v_mul_f32_e32 v209, v205, v165
	v_mul_f32_e32 v210, v206, v166
	v_mul_f32_e32 v211, v207, v167
	v_fmac_f32_e32 v234, v84, v208
	v_fmac_f32_e32 v234, v85, v209
	v_fmac_f32_e32 v234, v86, v210
	v_fmac_f32_e32 v234, v87, v211
